# ln_router L0 token loop: 16 LN/modulation parameter loads issued together before next-row prefetch, counted wait
# baseline (speedup 1.0000x reference)
.LBB0_835:
	s_waitcnt vmcnt(0)
	s_or_b64 exec, exec, s[2:3]
	s_and_b64 s[2:3], exec, s[14:15]
	s_or_b64 s[22:23], s[2:3], s[22:23]
	v_mov_b32_e32 v48, v72
	v_mov_b64_e32 v[28:29], v[0:1]
	v_mov_b64_e32 v[30:31], v[2:3]
	v_mov_b64_e32 v[24:25], v[4:5]
	v_mov_b64_e32 v[26:27], v[6:7]
	v_mov_b64_e32 v[20:21], v[8:9]
	v_mov_b64_e32 v[22:23], v[10:11]
	v_mov_b64_e32 v[16:17], v[12:13]
	v_mov_b64_e32 v[18:19], v[14:15]
	s_andn2_b64 exec, exec, s[22:23]
	s_cbranch_execz .LBB0_842
.LBB0_836:
	s_movk_i32 s2, 0xfff
	v_cmp_lt_i32_e32 vcc, s2, v48
	v_add_u32_e32 v72, s11, v48
	s_movk_i32 s2, 0x1fff
	v_cmp_gt_i32_e64 s[18:19], s10, v72
	v_cmp_lt_i32_e64 s[14:15], s2, v72
	v_add_f32_e32 v33, v28, v29
	v_add_f32_e32 v33, v33, v30
	v_add_f32_e32 v34, v24, v25
	v_add_f32_e32 v33, v33, v31
	v_add_f32_e32 v34, v34, v26
	v_add_f32_e32 v33, 0, v33
	v_add_f32_e32 v34, v34, v27
	v_add_f32_e32 v33, v33, v34
	v_add_f32_e32 v34, v20, v21
	v_add_f32_e32 v34, v34, v22
	v_add_f32_e32 v34, v34, v23
	v_add_f32_e32 v33, v33, v34
	v_add_f32_e32 v34, v16, v17
	v_add_f32_e32 v34, v34, v18
	v_add_f32_e32 v34, v34, v19
	v_add_f32_e32 v49, v33, v34
	v_pk_mul_f32 v[34:35], v[28:29], v[28:29]
	v_pk_mul_f32 v[38:39], v[24:25], v[24:25]
	v_pk_mul_f32 v[36:37], v[30:31], v[30:31]
	v_pk_mul_f32 v[40:41], v[26:27], v[26:27]
	v_pk_mul_f32 v[42:43], v[20:21], v[20:21]
	v_add_f32_e32 v38, v38, v39
	v_add_f32_e32 v34, v34, v35
	v_pk_mul_f32 v[44:45], v[22:23], v[22:23]
	v_add_f32_e32 v38, v38, v40
	v_add_f32_e32 v34, v34, v36
	v_add_f32_e32 v35, v42, v43
	v_add_f32_e32 v38, v38, v41
	v_add_f32_e32 v34, v34, v37
	v_add_f32_e32 v35, v35, v44
	v_pk_mul_f32 v[46:47], v[16:17], v[16:17]
	v_add_f32_e32 v34, v34, v38
	v_add_f32_e32 v35, v35, v45
	v_pk_mul_f32 v[74:75], v[18:19], v[18:19]
	v_add_f32_e32 v34, v34, v35
	v_add_f32_e32 v35, v46, v47
	v_add_f32_e32 v35, v35, v74
	v_add_f32_e32 v35, v35, v75
	v_add_f32_e32 v34, v34, v35
	v_add_u32_e32 v32, 0xfffff000, v48
	v_add_f32_dpp v35, v49, v49 row_ror:8 row_mask:0xf bank_mask:0xf bound_ctrl:1
	v_add_f32_dpp v34, v34, v34 row_ror:8 row_mask:0xf bank_mask:0xf bound_ctrl:1
	v_lshrrev_b32_e32 v32, 11, v32
	v_add_f32_dpp v35, v35, v35 row_ror:4 row_mask:0xf bank_mask:0xf bound_ctrl:1
	v_add_f32_dpp v34, v34, v34 row_ror:4 row_mask:0xf bank_mask:0xf bound_ctrl:1
	v_add_u32_e32 v32, 1, v32
	v_add_f32_dpp v35, v35, v35 row_ror:2 row_mask:0xf bank_mask:0xf bound_ctrl:1
	v_add_f32_dpp v34, v34, v34 row_ror:2 row_mask:0xf bank_mask:0xf bound_ctrl:1
	v_cndmask_b32_e32 v32, 0, v32, vcc
	v_add_f32_dpp v35, v35, v35 row_ror:1 row_mask:0xf bank_mask:0xf bound_ctrl:1
	v_mov_b32_e32 v36, v35
	v_add_f32_dpp v34, v34, v34 row_ror:1 row_mask:0xf bank_mask:0xf bound_ctrl:1
	s_nop 0
	v_permlane16_swap_b32_e32 v35, v36
	v_add_f32_e32 v35, v35, v36
	v_mov_b32_e32 v36, v34
	s_nop 1
	v_permlane16_swap_b32_e32 v34, v36
	v_add_f32_e32 v34, v34, v36
	s_movk_i32 s2, 0x6000
	v_mov_b32_e32 v37, v35
	v_mov_b32_e32 v36, v34
	v_mad_u64_u32 v[32:33], s[2:3], v32, s2, v[64:65]
	v_permlane32_swap_b32_e32 v35, v37
	v_permlane32_swap_b32_e32 v34, v36
	v_pk_add_f32 v[34:35], v[34:35], v[36:37]
	s_mov_b32 s2, 0x3a800000
	v_pk_mul_f32 v[74:75], v[34:35], s[2:3] op_sel_hi:[1,0]
	s_mov_b32 s2, 0x800000
	v_fma_f32 v34, -v75, v75, v74
	v_max_f32_e32 v34, 0, v34
	v_add_f32_e32 v34, 0x3727c5ac, v34
	v_cmp_gt_f32_e32 vcc, s2, v34
	v_mul_f32_e32 v35, 0x4b800000, v34
	s_mov_b64 s[2:3], 0x3000
	v_cndmask_b32_e32 v34, v34, v35, vcc
	v_rsq_f32_e32 v34, v34
	v_lshl_add_u64 v[80:81], v[32:33], 0, s[2:3]
	s_mov_b64 s[2:3], 0x4000
	v_lshl_add_u64 v[78:79], v[32:33], 0, s[2:3]
	v_mul_f32_e32 v35, 0x45800000, v34
	v_lshl_add_u64 v[40:41], v[80:81], 0, v[50:51]
	v_lshl_add_u64 v[44:45], v[78:79], 0, v[50:51]
	v_cndmask_b32_e32 v76, v34, v35, vcc
	v_lshl_add_u64 v[92:93], v[80:81], 0, v[66:67]
	v_lshl_add_u64 v[94:95], v[78:79], 0, v[66:67]
	v_lshl_add_u64 v[96:97], v[80:81], 0, v[68:69]
	v_lshl_add_u64 v[98:99], v[78:79], 0, v[68:69]
	v_lshl_add_u64 v[164:165], v[80:81], 0, v[70:71]
	v_lshl_add_u64 v[166:167], v[78:79], 0, v[70:71]
	global_load_dwordx4 v[100:103], v[54:55], off
	global_load_dwordx4 v[104:107], v[54:55], off offset:1024
	global_load_dwordx4 v[108:111], v[54:55], off offset:2048
	global_load_dwordx4 v[112:115], v[54:55], off offset:3072
	global_load_dwordx4 v[116:119], v[56:57], off
	global_load_dwordx4 v[120:123], v[56:57], off offset:1024
	global_load_dwordx4 v[124:127], v[56:57], off offset:2048
	global_load_dwordx4 v[128:131], v[56:57], off offset:3072
	global_load_dwordx4 v[132:135], v[40:41], off
	global_load_dwordx4 v[148:151], v[44:45], off
	global_load_dwordx4 v[136:139], v[92:93], off
	global_load_dwordx4 v[152:155], v[94:95], off
	global_load_dwordx4 v[140:143], v[96:97], off
	global_load_dwordx4 v[156:159], v[98:99], off
	global_load_dwordx4 v[144:147], v[164:165], off
	global_load_dwordx4 v[160:163], v[166:167], off
	s_and_b64 vcc, exec, s[18:19]
	s_cbranch_vccz .Lr6_dummy
	v_ashrrev_i32_e32 v73, 31, v72
	v_lshlrev_b64 v[0:1], 12, v[72:73]
	v_lshl_add_u64 v[12:13], v[58:59], 0, v[0:1]
	global_load_dwordx4 v[0:3], v[12:13], off
	global_load_dwordx4 v[4:7], v[12:13], off offset:1024
	global_load_dwordx4 v[8:11], v[12:13], off offset:2048
	s_nop 0
	global_load_dwordx4 v[12:15], v[12:13], off offset:3072
	s_branch .Lr6_join
.Lr6_dummy:
	global_load_dwordx4 v[0:3], v[54:55], off
	global_load_dwordx4 v[4:7], v[54:55], off
	global_load_dwordx4 v[8:11], v[54:55], off
	global_load_dwordx4 v[12:15], v[54:55], off
.Lr6_join:
	v_pk_add_f32 v[28:29], v[28:29], v[74:75] op_sel:[0,1] neg_lo:[0,1] neg_hi:[0,1]
	v_pk_add_f32 v[30:31], v[30:31], v[74:75] op_sel:[0,1] neg_lo:[0,1] neg_hi:[0,1]
	v_pk_mul_f32 v[28:29], v[28:29], v[76:77] op_sel_hi:[1,0]
	v_pk_mul_f32 v[30:31], v[30:31], v[76:77] op_sel_hi:[1,0]
	v_ashrrev_i32_e32 v49, 31, v48
	v_lshlrev_b64 v[82:83], 11, v[48:49]
	v_pk_add_f32 v[24:25], v[24:25], v[74:75] op_sel:[0,1] neg_lo:[0,1] neg_hi:[0,1]
	v_pk_add_f32 v[26:27], v[26:27], v[74:75] op_sel:[0,1] neg_lo:[0,1] neg_hi:[0,1]
	v_pk_mul_f32 v[24:25], v[24:25], v[76:77] op_sel_hi:[1,0]
	v_pk_mul_f32 v[26:27], v[26:27], v[76:77] op_sel_hi:[1,0]
	v_pk_add_f32 v[20:21], v[20:21], v[74:75] op_sel:[0,1] neg_lo:[0,1] neg_hi:[0,1]
	v_pk_add_f32 v[22:23], v[22:23], v[74:75] op_sel:[0,1] neg_lo:[0,1] neg_hi:[0,1]
	v_pk_mul_f32 v[20:21], v[20:21], v[76:77] op_sel_hi:[1,0]
	v_pk_mul_f32 v[22:23], v[22:23], v[76:77] op_sel_hi:[1,0]
	v_pk_add_f32 v[16:17], v[16:17], v[74:75] op_sel:[0,1] neg_lo:[0,1] neg_hi:[0,1]
	v_pk_add_f32 v[18:19], v[18:19], v[74:75] op_sel:[0,1] neg_lo:[0,1] neg_hi:[0,1]
	v_pk_mul_f32 v[16:17], v[16:17], v[76:77] op_sel_hi:[1,0]
	v_pk_mul_f32 v[18:19], v[18:19], v[76:77] op_sel_hi:[1,0]
	s_waitcnt vmcnt(4)
	v_pk_fma_f32 v[28:29], v[100:101], v[28:29], v[116:117]
	v_pk_add_f32 v[34:35], v[148:149], 1.0 op_sel_hi:[1,0]
	v_pk_fma_f32 v[30:31], v[102:103], v[30:31], v[118:119]
	v_pk_fma_f32 v[28:29], v[34:35], v[28:29], v[132:133]
	v_pk_add_f32 v[34:35], v[150:151], 1.0 op_sel_hi:[1,0]
	s_nop 0
	v_pk_fma_f32 v[30:31], v[30:31], v[34:35], v[134:135]
	v_lshl_add_u64 v[32:33], v[62:63], 0, v[82:83]
	v_cvt_pk_bf16_f32 v36, v28, v29
	v_cvt_pk_bf16_f32 v37, v30, v31
	global_store_dwordx2 v[32:33], v[36:37], off
	v_pk_fma_f32 v[24:25], v[104:105], v[24:25], v[120:121]
	v_pk_add_f32 v[34:35], v[152:153], 1.0 op_sel_hi:[1,0]
	v_pk_fma_f32 v[26:27], v[106:107], v[26:27], v[122:123]
	v_pk_fma_f32 v[24:25], v[34:35], v[24:25], v[136:137]
	v_pk_add_f32 v[34:35], v[154:155], 1.0 op_sel_hi:[1,0]
	s_nop 0
	v_pk_fma_f32 v[26:27], v[26:27], v[34:35], v[138:139]
	v_cvt_pk_bf16_f32 v36, v24, v25
	v_cvt_pk_bf16_f32 v37, v26, v27
	global_store_dwordx2 v[32:33], v[36:37], off offset:512
	v_pk_fma_f32 v[20:21], v[108:109], v[20:21], v[124:125]
	v_pk_add_f32 v[34:35], v[156:157], 1.0 op_sel_hi:[1,0]
	v_pk_fma_f32 v[22:23], v[110:111], v[22:23], v[126:127]
	v_pk_fma_f32 v[20:21], v[34:35], v[20:21], v[140:141]
	v_pk_add_f32 v[34:35], v[158:159], 1.0 op_sel_hi:[1,0]
	s_nop 0
	v_pk_fma_f32 v[22:23], v[22:23], v[34:35], v[142:143]
	v_cvt_pk_bf16_f32 v36, v20, v21
	v_cvt_pk_bf16_f32 v37, v22, v23
	global_store_dwordx2 v[32:33], v[36:37], off offset:1024
	v_pk_fma_f32 v[16:17], v[112:113], v[16:17], v[128:129]
	v_pk_add_f32 v[34:35], v[160:161], 1.0 op_sel_hi:[1,0]
	v_pk_fma_f32 v[18:19], v[114:115], v[18:19], v[130:131]
	v_pk_fma_f32 v[16:17], v[34:35], v[16:17], v[144:145]
	v_pk_add_f32 v[34:35], v[162:163], 1.0 op_sel_hi:[1,0]
	s_nop 0
	v_pk_fma_f32 v[18:19], v[18:19], v[34:35], v[146:147]
	v_cvt_pk_bf16_f32 v36, v16, v17
	v_cvt_pk_bf16_f32 v37, v18, v19
	global_store_dwordx2 v[32:33], v[36:37], off offset:1536
	ds_read_b128 v[32:35], v52
	s_waitcnt lgkmcnt(0)
	v_mul_f32_e32 v33, v29, v33
	v_fmac_f32_e32 v33, v28, v32
	v_fmac_f32_e32 v33, v30, v34
	v_fmac_f32_e32 v33, v31, v35
	v_add_f32_e32 v36, 0, v33
	ds_read_b128 v[32:35], v52 offset:1024
	s_waitcnt lgkmcnt(0)
	v_mul_f32_e32 v33, v25, v33
	v_fmac_f32_e32 v33, v24, v32
	v_fmac_f32_e32 v33, v26, v34
	v_fmac_f32_e32 v33, v27, v35
	v_add_f32_e32 v36, v36, v33
	ds_read_b128 v[32:35], v52 offset:2048
	s_waitcnt lgkmcnt(0)
	v_mul_f32_e32 v33, v21, v33
	v_fmac_f32_e32 v33, v20, v32
	v_fmac_f32_e32 v33, v22, v34
	v_fmac_f32_e32 v33, v23, v35
	v_add_f32_e32 v36, v36, v33
	ds_read_b128 v[32:35], v52 offset:3072
	s_waitcnt lgkmcnt(0)
	v_mul_f32_e32 v33, v17, v33
	v_fmac_f32_e32 v33, v16, v32
	v_fmac_f32_e32 v33, v18, v34
	v_fmac_f32_e32 v33, v19, v35
	v_add_f32_e32 v32, v36, v33
	ds_read_b128 v[34:37], v52 offset:7168
	ds_read_b128 v[38:41], v52 offset:6144
	ds_read_b128 v[42:45], v52 offset:5120
	ds_read_b128 v[78:81], v52 offset:4096
	s_waitcnt lgkmcnt(3)
	v_mul_f32_e32 v34, v16, v34
	s_waitcnt lgkmcnt(2)
	v_mul_f32_e32 v38, v20, v38
	s_waitcnt lgkmcnt(1)
	v_mul_f32_e32 v42, v24, v42
	s_waitcnt lgkmcnt(0)
	v_mul_f32_e32 v33, v28, v78
	v_fmac_f32_e32 v33, v29, v79
	v_fmac_f32_e32 v33, v30, v80
	v_fmac_f32_e32 v42, v25, v43
	v_fmac_f32_e32 v33, v31, v81
	v_fmac_f32_e32 v42, v26, v44
	v_fmac_f32_e32 v38, v21, v39
	v_add_f32_e32 v33, 0, v33
	v_fmac_f32_e32 v42, v27, v45
	v_fmac_f32_e32 v38, v22, v40
	v_fmac_f32_e32 v34, v17, v35
	v_add_f32_e32 v33, v42, v33
	v_fmac_f32_e32 v38, v23, v41
	v_fmac_f32_e32 v34, v18, v36
	v_add_f32_e32 v33, v38, v33
	v_fmac_f32_e32 v34, v19, v37
	v_add_f32_e32 v33, v34, v33
	ds_read_b128 v[34:37], v52 offset:8192
	ds_read_b128 v[38:41], v52 offset:9216
	ds_read_b128 v[42:45], v52 offset:10240
	s_waitcnt lgkmcnt(2)
	v_mul_f32_e32 v35, v29, v35
	s_waitcnt lgkmcnt(1)
	v_mul_f32_e32 v39, v25, v39
	v_fmac_f32_e32 v35, v28, v34
	v_fmac_f32_e32 v39, v24, v38
	v_fmac_f32_e32 v35, v30, v36
	v_fmac_f32_e32 v35, v31, v37
	v_fmac_f32_e32 v39, v26, v40
	v_add_f32_e32 v34, 0, v35
	v_fmac_f32_e32 v39, v27, v41
	v_add_f32_e32 v38, v34, v39
	ds_read_b128 v[34:37], v52 offset:11264
	s_waitcnt lgkmcnt(1)
	v_mul_f32_e32 v39, v21, v43
	v_fmac_f32_e32 v39, v20, v42
	v_fmac_f32_e32 v39, v22, v44
	v_fmac_f32_e32 v39, v23, v45
	v_add_f32_e32 v46, v38, v39
	ds_read_b128 v[38:41], v52 offset:13312
	ds_read_b128 v[42:45], v52 offset:12288
	s_waitcnt lgkmcnt(2)
	v_mul_f32_e32 v35, v17, v35
	v_fmac_f32_e32 v35, v16, v34
	v_fmac_f32_e32 v35, v18, v36
	v_fmac_f32_e32 v35, v19, v37
	v_add_f32_e32 v34, v46, v35
	ds_read_b128 v[78:81], v52 offset:15360
	ds_read_b128 v[88:91], v52 offset:14336
	s_waitcnt lgkmcnt(2)
	v_mul_f32_e32 v35, v28, v42
	v_fmac_f32_e32 v35, v29, v43
	v_mul_f32_e32 v36, v24, v38
	v_fmac_f32_e32 v35, v30, v44
	v_fmac_f32_e32 v36, v25, v39
	v_fmac_f32_e32 v35, v31, v45
	v_fmac_f32_e32 v36, v26, v40
	v_add_f32_e32 v35, 0, v35
	v_fmac_f32_e32 v36, v27, v41
	v_add_f32_e32 v35, v36, v35
	s_waitcnt lgkmcnt(0)
	v_mul_f32_e32 v36, v20, v88
	v_fmac_f32_e32 v36, v21, v89
	v_fmac_f32_e32 v36, v22, v90
	v_fmac_f32_e32 v36, v23, v91
	v_add_f32_e32 v35, v36, v35
	v_mul_f32_e32 v36, v16, v78
	v_fmac_f32_e32 v36, v17, v79
	v_fmac_f32_e32 v36, v18, v80
	v_fmac_f32_e32 v36, v19, v81
	v_add_f32_e32 v35, v36, v35
	ds_read_b128 v[36:39], v52 offset:16384
	ds_read_b128 v[40:43], v52 offset:17408
	ds_read_b128 v[44:47], v52 offset:18432
	s_waitcnt lgkmcnt(2)
	v_mul_f32_e32 v37, v29, v37
	s_waitcnt lgkmcnt(1)
	v_mul_f32_e32 v41, v25, v41
	v_fmac_f32_e32 v37, v28, v36
	v_fmac_f32_e32 v41, v24, v40
	v_fmac_f32_e32 v37, v30, v38
	v_fmac_f32_e32 v37, v31, v39
	v_fmac_f32_e32 v41, v26, v42
	v_add_f32_e32 v36, 0, v37
	v_fmac_f32_e32 v41, v27, v43
	v_add_f32_e32 v40, v36, v41
	ds_read_b128 v[36:39], v52 offset:19456
	s_waitcnt lgkmcnt(1)
	v_mul_f32_e32 v41, v21, v45
	v_fmac_f32_e32 v41, v20, v44
	v_fmac_f32_e32 v41, v22, v46
	v_fmac_f32_e32 v41, v23, v47
	v_add_f32_e32 v73, v40, v41
	ds_read_b128 v[40:43], v52 offset:21504
	ds_read_b128 v[44:47], v52 offset:20480
	s_waitcnt lgkmcnt(2)
	v_mul_f32_e32 v37, v17, v37
	v_fmac_f32_e32 v37, v16, v36
	v_fmac_f32_e32 v37, v18, v38
	v_fmac_f32_e32 v37, v19, v39
	v_add_f32_e32 v36, v73, v37
	ds_read_b128 v[78:81], v52 offset:23552
	ds_read_b128 v[88:91], v52 offset:22528
	s_waitcnt lgkmcnt(2)
	v_mul_f32_e32 v37, v28, v44
	v_fmac_f32_e32 v37, v29, v45
	v_mul_f32_e32 v38, v24, v40
	v_fmac_f32_e32 v37, v30, v46
	v_fmac_f32_e32 v38, v25, v41
	v_fmac_f32_e32 v37, v31, v47
	v_fmac_f32_e32 v38, v26, v42
	v_add_f32_e32 v37, 0, v37
	v_fmac_f32_e32 v38, v27, v43
	v_add_f32_e32 v37, v38, v37
	s_waitcnt lgkmcnt(0)
	v_mul_f32_e32 v38, v20, v88
	v_fmac_f32_e32 v38, v21, v89
	v_fmac_f32_e32 v38, v22, v90
	v_fmac_f32_e32 v38, v23, v91
	v_add_f32_e32 v37, v38, v37
	v_mul_f32_e32 v38, v16, v78
	v_fmac_f32_e32 v38, v17, v79
	v_fmac_f32_e32 v38, v18, v80
	v_fmac_f32_e32 v38, v19, v81
	v_add_f32_e32 v37, v38, v37
	ds_read_b128 v[38:41], v52 offset:24576
	ds_read_b128 v[42:45], v52 offset:25600
	ds_read_b128 v[78:81], v52 offset:26624
	s_waitcnt lgkmcnt(2)
	v_mul_f32_e32 v39, v29, v39
	s_waitcnt lgkmcnt(1)
	v_mul_f32_e32 v43, v25, v43
	v_fmac_f32_e32 v39, v28, v38
	v_fmac_f32_e32 v43, v24, v42
	v_fmac_f32_e32 v39, v30, v40
	v_fmac_f32_e32 v39, v31, v41
	v_fmac_f32_e32 v43, v26, v44
	v_add_f32_e32 v38, 0, v39
	v_fmac_f32_e32 v43, v27, v45
	v_add_f32_e32 v42, v38, v43
	ds_read_b128 v[38:41], v52 offset:27648
	s_waitcnt lgkmcnt(1)
	v_mul_f32_e32 v43, v21, v79
	v_fmac_f32_e32 v43, v20, v78
	v_fmac_f32_e32 v43, v22, v80
	v_fmac_f32_e32 v43, v23, v81
	s_waitcnt lgkmcnt(0)
	v_mul_f32_e32 v39, v17, v39
	v_fmac_f32_e32 v39, v16, v38
	v_add_f32_e32 v46, v42, v43
	v_fmac_f32_e32 v39, v18, v40
	ds_read_b128 v[42:45], v52 offset:29696
	ds_read_b128 v[78:81], v52 offset:28672
	v_fmac_f32_e32 v39, v19, v41
	v_add_f32_e32 v46, v46, v39
	ds_read_b128 v[38:41], v52 offset:31744
	ds_read_b128 v[88:91], v52 offset:30720
	s_waitcnt lgkmcnt(3)
	v_mul_f32_e32 v42, v24, v42
	s_waitcnt lgkmcnt(2)
	v_mul_f32_e32 v47, v28, v78
	v_fmac_f32_e32 v47, v29, v79
	v_fmac_f32_e32 v47, v30, v80
	v_fmac_f32_e32 v42, v25, v43
	s_waitcnt lgkmcnt(0)
	v_mul_f32_e32 v43, v20, v88
	v_fmac_f32_e32 v47, v31, v81
	v_fmac_f32_e32 v42, v26, v44
	v_fmac_f32_e32 v43, v21, v89
	v_mul_f32_e32 v38, v16, v38
	v_add_f32_e32 v47, 0, v47
	v_fmac_f32_e32 v42, v27, v45
	v_fmac_f32_e32 v43, v22, v90
	v_fmac_f32_e32 v38, v17, v39
	v_add_f32_e32 v42, v42, v47
	v_fmac_f32_e32 v43, v23, v91
	v_fmac_f32_e32 v38, v18, v40
	v_add_f32_e32 v42, v43, v42
	v_fmac_f32_e32 v38, v19, v41
	v_add_f32_e32 v47, v38, v42
	ds_read_b128 v[38:41], v52 offset:32768
	ds_read_b128 v[42:45], v52 offset:33792
	ds_read_b128 v[78:81], v52 offset:34816
	s_waitcnt lgkmcnt(2)
	v_mul_f32_e32 v39, v29, v39
	s_waitcnt lgkmcnt(1)
	v_mul_f32_e32 v43, v25, v43
	v_fmac_f32_e32 v39, v28, v38
	v_fmac_f32_e32 v43, v24, v42
	v_fmac_f32_e32 v39, v30, v40
	v_fmac_f32_e32 v39, v31, v41
	v_fmac_f32_e32 v43, v26, v44
	v_add_f32_e32 v38, 0, v39
	v_fmac_f32_e32 v43, v27, v45
	v_add_f32_e32 v42, v38, v43
	ds_read_b128 v[38:41], v52 offset:35840
	s_waitcnt lgkmcnt(1)
	v_mul_f32_e32 v43, v21, v79
	v_fmac_f32_e32 v43, v20, v78
	v_fmac_f32_e32 v43, v22, v80
	v_fmac_f32_e32 v43, v23, v81
	s_waitcnt lgkmcnt(0)
	v_mul_f32_e32 v39, v17, v39
	v_fmac_f32_e32 v39, v16, v38
	v_add_f32_e32 v73, v42, v43
	v_fmac_f32_e32 v39, v18, v40
	ds_read_b128 v[42:45], v52 offset:37888
	ds_read_b128 v[78:81], v52 offset:36864
	v_fmac_f32_e32 v39, v19, v41
	v_add_f32_e32 v73, v73, v39
	ds_read_b128 v[38:41], v52 offset:39936
	ds_read_b128 v[88:91], v52 offset:38912
	s_waitcnt lgkmcnt(3)
	v_mul_f32_e32 v42, v24, v42
	s_waitcnt lgkmcnt(2)
	v_mul_f32_e32 v74, v28, v78
	v_fmac_f32_e32 v74, v29, v79
	v_fmac_f32_e32 v74, v30, v80
	v_fmac_f32_e32 v42, v25, v43
	s_waitcnt lgkmcnt(0)
	v_mul_f32_e32 v43, v20, v88
	v_fmac_f32_e32 v74, v31, v81
	v_fmac_f32_e32 v42, v26, v44
	v_fmac_f32_e32 v43, v21, v89
	v_mul_f32_e32 v38, v16, v38
	v_add_f32_e32 v74, 0, v74
	v_fmac_f32_e32 v42, v27, v45
	v_fmac_f32_e32 v43, v22, v90
	v_fmac_f32_e32 v38, v17, v39
	v_add_f32_e32 v42, v42, v74
	v_fmac_f32_e32 v43, v23, v91
	v_fmac_f32_e32 v38, v18, v40
	v_add_f32_e32 v42, v43, v42
	v_fmac_f32_e32 v38, v19, v41
	v_add_f32_e32 v74, v38, v42
	ds_read_b128 v[38:41], v52 offset:40960
	ds_read_b128 v[42:45], v52 offset:41984
	ds_read_b128 v[78:81], v52 offset:43008
	s_waitcnt lgkmcnt(2)
	v_mul_f32_e32 v39, v29, v39
	s_waitcnt lgkmcnt(1)
	v_mul_f32_e32 v43, v25, v43
	v_fmac_f32_e32 v39, v28, v38
	v_fmac_f32_e32 v43, v24, v42
	v_fmac_f32_e32 v39, v30, v40
	v_fmac_f32_e32 v39, v31, v41
	v_fmac_f32_e32 v43, v26, v44
	v_add_f32_e32 v38, 0, v39
	v_fmac_f32_e32 v43, v27, v45
	v_add_f32_e32 v42, v38, v43
	ds_read_b128 v[38:41], v52 offset:44032
	s_waitcnt lgkmcnt(1)
	v_mul_f32_e32 v43, v21, v79
	v_fmac_f32_e32 v43, v20, v78
	v_fmac_f32_e32 v43, v22, v80
	v_fmac_f32_e32 v43, v23, v81
	s_waitcnt lgkmcnt(0)
	v_mul_f32_e32 v39, v17, v39
	v_fmac_f32_e32 v39, v16, v38
	v_add_f32_e32 v75, v42, v43
	v_fmac_f32_e32 v39, v18, v40
	ds_read_b128 v[42:45], v52 offset:46080
	ds_read_b128 v[78:81], v52 offset:45056
	v_fmac_f32_e32 v39, v19, v41
	v_add_f32_e32 v75, v75, v39
	ds_read_b128 v[38:41], v52 offset:48128
	ds_read_b128 v[88:91], v52 offset:47104
	s_waitcnt lgkmcnt(3)
	v_mul_f32_e32 v42, v24, v42
	s_waitcnt lgkmcnt(2)
	v_mul_f32_e32 v76, v28, v78
	v_fmac_f32_e32 v76, v29, v79
	v_fmac_f32_e32 v76, v30, v80
	v_fmac_f32_e32 v42, v25, v43
	s_waitcnt lgkmcnt(0)
	v_mul_f32_e32 v43, v20, v88
	v_fmac_f32_e32 v76, v31, v81
	v_fmac_f32_e32 v42, v26, v44
	v_fmac_f32_e32 v43, v21, v89
	v_mul_f32_e32 v38, v16, v38
	v_add_f32_e32 v76, 0, v76
	v_fmac_f32_e32 v42, v27, v45
	v_fmac_f32_e32 v43, v22, v90
	v_fmac_f32_e32 v38, v17, v39
	v_add_f32_e32 v42, v42, v76
	v_fmac_f32_e32 v43, v23, v91
	v_fmac_f32_e32 v38, v18, v40
	v_add_f32_e32 v42, v43, v42
	v_fmac_f32_e32 v38, v19, v41
	v_add_f32_e32 v76, v38, v42
	ds_read_b128 v[38:41], v52 offset:49152
	ds_read_b128 v[42:45], v52 offset:50176
	ds_read_b128 v[78:81], v52 offset:51200
	s_waitcnt lgkmcnt(2)
	v_mul_f32_e32 v39, v29, v39
	s_waitcnt lgkmcnt(1)
	v_mul_f32_e32 v43, v25, v43
	v_fmac_f32_e32 v39, v28, v38
	v_fmac_f32_e32 v43, v24, v42
	v_fmac_f32_e32 v39, v30, v40
	v_fmac_f32_e32 v39, v31, v41
	v_fmac_f32_e32 v43, v26, v44
	v_add_f32_e32 v38, 0, v39
	v_fmac_f32_e32 v43, v27, v45
	v_add_f32_e32 v42, v38, v43
	ds_read_b128 v[38:41], v52 offset:52224
	s_waitcnt lgkmcnt(1)
	v_mul_f32_e32 v43, v21, v79
	v_fmac_f32_e32 v43, v20, v78
	v_fmac_f32_e32 v43, v22, v80
	v_fmac_f32_e32 v43, v23, v81
	s_waitcnt lgkmcnt(0)
	v_mul_f32_e32 v39, v17, v39
	v_fmac_f32_e32 v39, v16, v38
	v_add_f32_e32 v82, v42, v43
	v_fmac_f32_e32 v39, v18, v40
	ds_read_b128 v[42:45], v52 offset:54272
	ds_read_b128 v[78:81], v52 offset:53248
	v_fmac_f32_e32 v39, v19, v41
	v_add_f32_e32 v82, v82, v39
	ds_read_b128 v[38:41], v52 offset:56320
	ds_read_b128 v[88:91], v52 offset:55296
	s_waitcnt lgkmcnt(3)
	v_mul_f32_e32 v42, v24, v42
	s_waitcnt lgkmcnt(2)
	v_mul_f32_e32 v78, v28, v78
	v_fmac_f32_e32 v78, v29, v79
	v_fmac_f32_e32 v78, v30, v80
	v_fmac_f32_e32 v42, v25, v43
	s_waitcnt lgkmcnt(0)
	v_mul_f32_e32 v43, v20, v88
	v_fmac_f32_e32 v78, v31, v81
	v_fmac_f32_e32 v42, v26, v44
	v_fmac_f32_e32 v43, v21, v89
	v_mul_f32_e32 v38, v16, v38
	v_add_f32_e32 v78, 0, v78
	v_fmac_f32_e32 v42, v27, v45
	v_fmac_f32_e32 v43, v22, v90
	v_fmac_f32_e32 v38, v17, v39
	v_add_f32_e32 v42, v42, v78
	v_fmac_f32_e32 v43, v23, v91
	v_fmac_f32_e32 v38, v18, v40
	v_add_f32_e32 v42, v43, v42
	v_fmac_f32_e32 v38, v19, v41
	v_add_f32_e32 v83, v38, v42
	ds_read_b128 v[38:41], v52 offset:57344
	ds_read_b128 v[42:45], v52 offset:58368
	ds_read_b128 v[78:81], v52 offset:59392
	s_waitcnt lgkmcnt(2)
	v_mul_f32_e32 v39, v29, v39
	s_waitcnt lgkmcnt(1)
	v_mul_f32_e32 v43, v25, v43
	v_fmac_f32_e32 v39, v28, v38
	v_fmac_f32_e32 v43, v24, v42
	v_fmac_f32_e32 v39, v30, v40
	v_fmac_f32_e32 v39, v31, v41
	v_fmac_f32_e32 v43, v26, v44
	v_add_f32_e32 v38, 0, v39
	v_fmac_f32_e32 v43, v27, v45
	v_add_f32_e32 v42, v38, v43
	ds_read_b128 v[38:41], v52 offset:60416
	s_waitcnt lgkmcnt(1)
	v_mul_f32_e32 v43, v21, v79
	v_fmac_f32_e32 v43, v20, v78
	v_fmac_f32_e32 v43, v22, v80
	v_fmac_f32_e32 v43, v23, v81
	s_waitcnt lgkmcnt(0)
	v_mul_f32_e32 v39, v17, v39
	v_fmac_f32_e32 v39, v16, v38
	v_add_f32_e32 v87, v42, v43
	v_fmac_f32_e32 v39, v18, v40
	ds_read_b128 v[42:45], v52 offset:62464
	ds_read_b128 v[78:81], v52 offset:61440
	v_fmac_f32_e32 v39, v19, v41
	v_add_f32_e32 v87, v87, v39
	ds_read_b128 v[38:41], v52 offset:64512
	ds_read_b128 v[88:91], v52 offset:63488
	s_waitcnt lgkmcnt(3)
	v_mul_f32_e32 v24, v24, v42
	s_waitcnt lgkmcnt(2)
	v_mul_f32_e32 v28, v28, v78
	v_fmac_f32_e32 v28, v29, v79
	v_fmac_f32_e32 v28, v30, v80
	v_fmac_f32_e32 v24, v25, v43
	s_waitcnt lgkmcnt(0)
	v_mul_f32_e32 v20, v20, v88
	v_fmac_f32_e32 v28, v31, v81
	v_fmac_f32_e32 v24, v26, v44
	v_fmac_f32_e32 v20, v21, v89
	v_mul_f32_e32 v16, v16, v38
	v_add_f32_e32 v28, 0, v28
	v_fmac_f32_e32 v24, v27, v45
	v_fmac_f32_e32 v20, v22, v90
	v_fmac_f32_e32 v16, v17, v39
	v_add_f32_e32 v24, v24, v28
	v_fmac_f32_e32 v20, v23, v91
	v_fmac_f32_e32 v16, v18, v40
	v_add_f32_e32 v20, v20, v24
	v_fmac_f32_e32 v16, v19, v41
	v_add_f32_e32 v16, v16, v20
	v_cndmask_b32_e64 v18, v32, v73, s[34:35]
	v_mov_b32_e32 v19, v18
	s_nop 1
	v_permlane32_swap_b32_e32 v18, v19
	v_cndmask_b32_e64 v18, v18, v19, s[34:35]
	v_cndmask_b32_e64 v19, v33, v74, s[34:35]
	v_mov_b32_e32 v20, v19
	s_nop 1
	v_permlane32_swap_b32_e32 v19, v20
	v_cndmask_b32_e64 v19, v19, v20, s[34:35]
	v_cndmask_b32_e64 v20, v34, v75, s[34:35]
	v_mov_b32_e32 v21, v20
	s_nop 1
	v_permlane32_swap_b32_e32 v20, v21
	v_cndmask_b32_e64 v20, v20, v21, s[34:35]
	v_cndmask_b32_e64 v21, v35, v76, s[34:35]
	v_mov_b32_e32 v22, v21
	s_nop 1
	v_permlane32_swap_b32_e32 v21, v22
	v_cndmask_b32_e64 v21, v21, v22, s[34:35]
	v_cndmask_b32_e64 v22, v36, v82, s[34:35]
	v_mov_b32_e32 v23, v22
	s_nop 1
	v_permlane32_swap_b32_e32 v22, v23
	v_cndmask_b32_e64 v17, v73, v32, s[34:35]
	v_cndmask_b32_e64 v22, v22, v23, s[34:35]
	v_cndmask_b32_e64 v23, v37, v83, s[34:35]
	v_add_f32_e32 v17, v17, v18
	v_cndmask_b32_e64 v18, v74, v33, s[34:35]
	v_mov_b32_e32 v24, v23
	v_add_f32_e32 v18, v18, v19
	v_cndmask_b32_e64 v19, v75, v34, s[34:35]
	v_permlane32_swap_b32_e32 v23, v24
	v_add_f32_e32 v19, v19, v20
	v_cndmask_b32_e64 v20, v76, v35, s[34:35]
	v_cndmask_b32_e64 v23, v23, v24, s[34:35]
	v_cndmask_b32_e64 v24, v46, v87, s[34:35]
	v_add_f32_e32 v20, v20, v21
	v_cndmask_b32_e64 v21, v82, v36, s[34:35]
	v_mov_b32_e32 v25, v24
	v_add_f32_e32 v21, v21, v22
	v_cndmask_b32_e64 v22, v83, v37, s[34:35]
	v_permlane32_swap_b32_e32 v24, v25
	v_add_f32_e32 v22, v22, v23
	v_cndmask_b32_e64 v23, v87, v46, s[34:35]
	v_cndmask_b32_e64 v24, v24, v25, s[34:35]
	v_add_f32_e32 v23, v23, v24
	v_cndmask_b32_e64 v24, v16, v47, s[34:35]
	v_cndmask_b32_e64 v16, v47, v16, s[34:35]
	v_mov_b32_e32 v25, v16
	s_nop 1
	v_permlane32_swap_b32_e32 v16, v25
	v_cndmask_b32_e64 v16, v16, v25, s[34:35]
	v_add_f32_e32 v16, v24, v16
	v_cndmask_b32_e64 v24, v21, v17, s[4:5]
	v_cndmask_b32_e64 v17, v17, v21, s[4:5]
	v_mov_b32_e32 v21, v17
	s_nop 1
	v_permlane16_swap_b32_e32 v17, v21
	v_cndmask_b32_e64 v17, v17, v21, s[4:5]
	v_cndmask_b32_e64 v21, v22, v18, s[4:5]
	v_cndmask_b32_e64 v18, v18, v22, s[4:5]
	v_mov_b32_e32 v22, v18
	s_nop 1
	v_permlane16_swap_b32_e32 v18, v22
	v_cndmask_b32_e64 v18, v18, v22, s[4:5]
	v_add_f32_e32 v18, v21, v18
	v_cndmask_b32_e64 v21, v23, v19, s[4:5]
	v_cndmask_b32_e64 v19, v19, v23, s[4:5]
	v_mov_b32_e32 v22, v19
	s_nop 1
	v_permlane16_swap_b32_e32 v19, v22
	v_cndmask_b32_e64 v19, v19, v22, s[4:5]
	v_add_f32_e32 v19, v21, v19
	v_cndmask_b32_e64 v21, v16, v20, s[4:5]
	v_cndmask_b32_e64 v16, v20, v16, s[4:5]
	v_mov_b32_e32 v20, v16
	s_nop 1
	v_permlane16_swap_b32_e32 v16, v20
	v_cndmask_b32_e64 v16, v16, v20, s[4:5]
	v_add_f32_e32 v17, v24, v17
	v_add_f32_e32 v16, v21, v16
	v_cndmask_b32_e64 v20, v17, v19, s[6:7]
	v_cndmask_b32_e64 v21, v18, v16, s[6:7]
	ds_bpermute_b32 v20, v77, v20
	ds_bpermute_b32 v21, v77, v21
	v_cndmask_b32_e64 v17, v19, v17, s[6:7]
	v_cndmask_b32_e64 v16, v16, v18, s[6:7]
	s_mov_b32 s2, 0x3fb8aa3b
	s_waitcnt lgkmcnt(1)
	v_add_f32_e32 v17, v17, v20
	s_waitcnt lgkmcnt(0)
	v_add_f32_e32 v16, v16, v21
	v_cndmask_b32_e64 v18, v17, v16, s[8:9]
	ds_bpermute_b32 v18, v84, v18
	v_cndmask_b32_e64 v16, v16, v17, s[8:9]
	s_waitcnt lgkmcnt(0)
	v_add_f32_e32 v16, v16, v18
	ds_bpermute_b32 v17, v85, v16
	s_waitcnt lgkmcnt(0)
	v_add_f32_e32 v16, v16, v17
	ds_bpermute_b32 v17, v86, v16
	s_waitcnt lgkmcnt(0)
	v_add_f32_e32 v16, v16, v17
	ds_bpermute_b32 v17, v77, v16
	s_waitcnt lgkmcnt(0)
	v_max_f32_e32 v17, v17, v17
	v_max_f32_e32 v17, v16, v17
	ds_bpermute_b32 v18, v84, v17
	s_waitcnt lgkmcnt(0)
	v_max_f32_e32 v18, v18, v18
	v_max_f32_e32 v17, v17, v18
	v_mov_b32_e32 v18, v17
	s_nop 1
	v_permlane16_swap_b32_e32 v17, v18
	v_max_f32_e32 v18, v18, v18
	v_max_f32_e32 v17, v17, v17
	v_max_f32_e32 v17, v17, v18
	v_mov_b32_e32 v18, v17
	s_nop 1
	v_permlane32_swap_b32_e32 v17, v18
	v_max_f32_e32 v18, v18, v18
	v_max_f32_e32 v17, v17, v17
	v_max_f32_e32 v17, v17, v18
	v_sub_f32_e32 v16, v16, v17
	v_mul_f32_e32 v17, 0x3fb8aa3b, v16
	v_fma_f32 v18, v16, s2, -v17
	v_rndne_f32_e32 v19, v17
	v_fmac_f32_e32 v18, 0x32a5705f, v16
	v_sub_f32_e32 v17, v17, v19
	v_add_f32_e32 v17, v17, v18
	v_exp_f32_e32 v17, v17
	v_cvt_i32_f32_e32 v18, v19
	s_mov_b32 s2, 0xc2ce8ed0
	v_cmp_ngt_f32_e32 vcc, s2, v16
	s_mov_b32 s2, 0x42b17218
	v_ldexp_f32 v17, v17, v18
	v_cndmask_b32_e32 v17, 0, v17, vcc
	v_cmp_nlt_f32_e32 vcc, s2, v16
	s_nop 1
	v_cndmask_b32_e32 v16, v53, v17, vcc
	ds_bpermute_b32 v17, v77, v16
	s_waitcnt lgkmcnt(0)
	v_add_f32_e32 v17, v16, v17
	ds_bpermute_b32 v18, v84, v17
	s_waitcnt lgkmcnt(0)
	v_add_f32_e32 v17, v17, v18
	v_mov_b32_e32 v18, v17
	s_nop 1
	v_permlane16_swap_b32_e32 v17, v18
	v_add_f32_e32 v17, v17, v18
	v_mov_b32_e32 v18, v17
	s_nop 1
	v_permlane32_swap_b32_e32 v17, v18
	s_and_saveexec_b64 s[2:3], s[0:1]
	s_cbranch_execz .LBB0_840
	v_add_f32_e32 v17, v17, v18
	v_div_scale_f32 v18, s[18:19], v17, v17, v16
	v_rcp_f32_e32 v19, v18
	v_div_scale_f32 v20, vcc, v16, v17, v16
	v_fma_f32 v21, -v18, v19, 1.0
	v_fmac_f32_e32 v19, v21, v19
	v_mul_f32_e32 v21, v20, v19
	v_fma_f32 v22, -v18, v21, v20
	v_fmac_f32_e32 v21, v22, v19
	v_fma_f32 v18, -v18, v21, v20
	v_div_fmas_f32 v18, v18, v19, v21
	v_div_fixup_f32 v18, v18, v17, v16
	v_lshlrev_b64 v[16:17], 6, v[48:49]
	v_lshl_add_u64 v[16:17], v[60:61], 0, v[16:17]
	global_store_dword v[16:17], v18, off
